# tail-workgroup row phase: touch-prefetch all rows of the iteration at loop top so the later serial loads hit cache
# baseline (speedup 1.0000x reference)
; __device__ __forceinline__ bf16* hrow16(unsigned char* ws, int r) { return (bf16*)(ws + WS_H16) + ((size_t)r << 10); }
; __device__ __forceinline__ void unpack8(const u32x4 w, float* v) { v[0] = bflo(w.x); v[1] = bfhi(w.x); v[2] = bflo(w.y); v[3] = bfhi(w.y); v[4] = bflo(w.z); v[5] = bfhi(w.z); v[6] = bflo(w.w); v[7] = bfhi(w.w); }
; __device__ __forceinline__ void row_res(KP kp, int gpost_in, int layer, bool has_next, int wid0, int row0, int row1, int b0, int nb, int tailp, bool pooled) {
;     ...
;     for (int base = row0 + ((int)blockIdx.x - b0) * 16 + wid; base < row1; base += nb * 16) {
;         float m[2][2][8], h[2][2][8]; float ss[2] = {0.f, 0.f};
; #pragma unroll
;         for (int r = 0; r < 2; ++r) { const int row = base + 8 * r; bf16* hp = hrow16(ws, row);
; #pragma unroll
;             for (int c = 0; c < 2; ++c) {
;                 if (tailp) { const bf16* t0 = (const bf16*)(ws + WS_MXT) + (size_t)(row - 128 * 256) * DM + c * 512 + lane * 8; unpack8(*(const u32x4*)t0, m[r][c]);
;                     for (int q = 1; q < tailp; ++q) { float m2[8]; unpack8(*(const u32x4*)(t0 + (size_t)q * 256 * 1024), m2);
; #pragma unroll
;                         for (int j = 0; j < 8; ++j) m[r][c][j] += m2[j]; } }
;                 else if (pooled) { const int t = row % LL, win = 2 << (c * 2 + (lane >> 5)), cnt = (t + 1) < win ? (t + 1) : win; const bf16* zp = MX + (size_t)row * DM + c * 512 + lane * 8;
;                     float z0[8], sum[8]; unpack8(*(const u32x4*)zp, z0);
; #pragma unroll
;                     for (int j = 0; j < 8; ++j) sum[j] = z0[j];
;                     for (int d = 1; d < cnt; ++d) { float zd[8]; unpack8(*(const u32x4*)(zp - (size_t)d * DM), zd);
; #pragma unroll
;                         for (int j = 0; j < 8; ++j) sum[j] += zd[j]; }
;                     const float inv = 1.0f / (float)cnt;
; #pragma unroll
;                     for (int j = 0; j < 8; ++j) m[r][c][j] = sum[j] * inv - z0[j]; }
;                 else { const u32x4 w = *(const u32x4*)(MX + (size_t)row * DM + c * 512 + lane * 8); unpack8(w, m[r][c]); }
;                 unpack8(*(const u32x4*)(hp + c * 512 + lane * 8), h[r][c]);
.LBB0_864:
	v_mul_hi_i32 v4, v38, s62
	v_lshrrev_b32_e32 v5, 31, v4
	v_ashrrev_i32_e32 v4, 7, v4
	v_add_u32_e32 v60, v4, v5
	v_ashrrev_i32_e32 v39, 31, v38
	v_mul_i32_i24_e32 v4, 0x810, v60
	v_lshlrev_b64 v[2:3], 11, v[38:39]
	v_sub_u32_e32 v4, v38, v4
	v_lshl_add_u64 v[6:7], v[46:47], 0, v[2:3]
	s_mov_b64 s[94:95], 0x4000
	v_lshl_add_u64 v[118:119], v[46:47], 0, v[2:3]
	v_lshl_add_u64 v[120:121], v[42:43], 0, v[2:3]
	global_load_dword v126, v[118:119], off
	global_load_dword v127, v[118:119], off offset:1024
	v_lshl_add_u64 v[122:123], v[118:119], 0, s[94:95]
	global_load_dword v128, v[120:121], off
	global_load_dword v129, v[120:121], off offset:1024
	v_lshl_add_u64 v[124:125], v[120:121], 0, s[94:95]
	global_load_dword v130, v[122:123], off
	global_load_dword v131, v[122:123], off offset:1024
	global_load_dword v132, v[124:125], off
	global_load_dword v133, v[124:125], off offset:1024
	global_load_dword v134, v[48:49], off
	global_load_dword v135, v[48:49], off offset:2048
	v_lshl_add_u64 v[118:119], v[44:45], 0, v[2:3]
	s_mov_b32 s94, 0xfc000000
	s_mov_b32 s95, -1
	v_lshl_add_u64 v[118:119], v[118:119], 0, s[94:95]
	s_mov_b64 s[94:95], 0x80000
	global_load_dword v136, v[118:119], off
	global_load_dword v137, v[118:119], off offset:1024
	v_lshl_add_u64 v[120:121], v[118:119], 0, s[94:95]
	s_mov_b64 s[94:95], 0x4000
	global_load_dword v138, v[120:121], off
	global_load_dword v139, v[120:121], off offset:1024
	v_lshl_add_u64 v[118:119], v[118:119], 0, s[94:95]
	v_lshl_add_u64 v[120:121], v[120:121], 0, s[94:95]
	global_load_dword v140, v[118:119], off
	global_load_dword v141, v[118:119], off offset:1024
	global_load_dword v142, v[120:121], off
	global_load_dword v143, v[120:121], off offset:1024
	v_add_u32_e32 v16, 1, v4
	s_mov_b64 s[4:5], -1
	s_and_b64 vcc, exec, s[26:27]
	s_cbranch_vccz .LBB0_874
	global_load_dwordx4 v[8:11], v[6:7], off
	s_and_b64 vcc, exec, s[28:29]
	s_waitcnt vmcnt(0)
	v_lshlrev_b32_e32 v22, 16, v8
	s_waitcnt lgkmcnt(0)
	v_and_b32_e32 v23, 0xffff0000, v8
	v_lshlrev_b32_e32 v24, 16, v9
	v_and_b32_e32 v25, 0xffff0000, v9
	v_lshlrev_b32_e32 v26, 16, v10
	v_and_b32_e32 v27, 0xffff0000, v10
	v_lshlrev_b32_e32 v28, 16, v11
	v_and_b32_e32 v29, 0xffff0000, v11
	s_cbranch_vccz .LBB0_867
	s_mov_b64 s[4:5], 0
